# P0: RMSNorm gain vector g1 hoisted out of the row loop (4 loads + 4 vmcnt(0) round trips per iteration removed)
# speedup vs baseline: 1.0153x; 1.0025x over previous
.Lmy_p0_b43:
	v_mov_b32_e32 v35, 0
	v_mov_b32_e32 v37, v35
	v_lshl_add_u64 v[2:3], s[16:17], 0, v[36:37]
	s_mov_b64 s[0:1], 0x3a00000
	v_lshl_add_u64 v[40:41], v[2:3], 0, s[0:1]
	s_lshl_b32 s0, s33, 4
	s_ashr_i32 s5, s4, 31
	s_ashr_i32 s1, s0, 31
	v_lshl_add_u64 v[38:39], s[8:9], 0, v[34:35]
	global_load_dwordx4 v[88:91], v[38:39], off
	global_load_dwordx4 v[92:95], v[38:39], off offset:1024
	global_load_dwordx4 v[96:99], v[38:39], off offset:2048
	global_load_dwordx4 v[100:103], v[38:39], off offset:3072
	s_lshl_b64 s[6:7], s[4:5], 10
	s_lshl_b64 s[8:9], s[0:1], 10
	s_lshl_b64 s[2:3], s[4:5], 12
	s_add_u32 s10, s14, s2
	s_addc_u32 s11, s15, s3
	s_lshl_b64 s[18:19], s[0:1], 12
	s_lshl_b64 s[2:3], s[4:5], 11
	s_add_u32 s20, s16, s2
	s_addc_u32 s21, s17, s3
	s_add_i32 s2, s4, s25
	s_ashr_i32 s3, s2, 31
	s_lshl_b64 s[22:23], s[0:1], 11
	s_lshl_b64 s[26:27], s[2:3], 11
	s_add_u32 s16, s16, s26
	v_mbcnt_lo_u32_b32 v1, -1, 0
	s_addc_u32 s17, s17, s27
	s_lshl_b64 s[2:3], s[2:3], 12
	v_mbcnt_hi_u32_b32 v1, -1, v1
	s_add_u32 s14, s14, s2
	v_and_b32_e32 v2, 64, v1
	s_addc_u32 s15, s15, s3
	v_mov_b32_e32 v42, 0x358637bd
	s_mov_b32 s24, 0x3a800000
	s_mov_b32 s1, 0x800000
	s_mov_b32 s5, 0xffff0000
	s_mov_b32 s29, 0x3a00000
	v_add_u32_e32 v43, 64, v2
	v_xor_b32_e32 v46, 1, v1
	v_xor_b32_e32 v47, 2, v1
	v_xor_b32_e32 v48, 4, v1
	v_xor_b32_e32 v49, 8, v1
	v_xor_b32_e32 v50, 16, v1
	v_xor_b32_e32 v51, 32, v1
	v_mov_b32_e32 v52, 1
	s_branch .LBB0_45

.LBB0_47:
	s_andn2_b64 vcc, exec, s[2:3]
	s_mov_b64 s[2:3], s[6:7]
	s_cbranch_vccnz .LBB0_44
	global_load_dwordx4 v[30:33], v[10:11], off
	global_load_dwordx4 v[22:25], v[10:11], off offset:1024
	global_load_dwordx4 v[6:9], v[10:11], off offset:3072
	global_load_dwordx4 v[14:17], v[10:11], off offset:2048
	v_lshl_add_u64 v[54:55], s[14:15], 0, v[34:35]
	global_load_dwordx4 v[26:29], v[54:55], off
	global_load_dwordx4 v[18:21], v[54:55], off offset:1024
	global_load_dwordx4 v[2:5], v[54:55], off offset:3072
	global_load_dwordx4 v[10:13], v[54:55], off offset:2048
	v_cmp_lt_i32_e32 vcc, v46, v43
	s_ashr_i32 s27, s26, 31
	v_cndmask_b32_e32 v53, v1, v46, vcc
	v_lshlrev_b32_e32 v53, 2, v53
	v_cmp_lt_i32_e32 vcc, v47, v43
	s_waitcnt vmcnt(7)
	v_pk_mul_f32 v[58:59], v[32:33], v[32:33]
	v_pk_mul_f32 v[60:61], v[30:31], v[30:31]
	s_waitcnt vmcnt(6)
	v_pk_mul_f32 v[62:63], v[24:25], v[24:25]
	v_pk_mul_f32 v[64:65], v[22:23], v[22:23]
	s_waitcnt vmcnt(4)
	v_mul_f32_e32 v66, v15, v15
	v_mul_f32_e32 v68, v17, v17
	v_pk_mov_b32 v[70:71], v[60:61], v[58:59] op_sel:[1,0]
	v_mov_b32_e32 v61, v59
	s_waitcnt vmcnt(3)
	v_pk_mul_f32 v[58:59], v[28:29], v[28:29]
	v_pk_mul_f32 v[72:73], v[26:27], v[26:27]
	v_pk_mov_b32 v[74:75], v[64:65], v[62:63] op_sel:[1,0]
	v_mov_b32_e32 v65, v63
	s_waitcnt vmcnt(2)
	v_pk_mul_f32 v[62:63], v[20:21], v[20:21]
	v_pk_mul_f32 v[76:77], v[18:19], v[18:19]
	v_mul_f32_e32 v82, v8, v8
	v_mul_f32_e32 v83, v9, v9
	v_pk_fma_f32 v[66:67], v[14:15], v[14:15], v[66:67] op_sel_hi:[1,1,0]
	v_pk_fma_f32 v[68:69], v[16:17], v[16:17], v[68:69] op_sel_hi:[1,1,0]
	v_pk_add_f32 v[60:61], v[70:71], v[60:61]
	v_pk_mov_b32 v[70:71], v[72:73], v[58:59] op_sel:[1,0]
	v_mov_b32_e32 v73, v59
	v_pk_add_f32 v[58:59], v[74:75], v[64:65]
	v_pk_mov_b32 v[64:65], v[76:77], v[62:63] op_sel:[1,0]
	v_mov_b32_e32 v77, v63
	v_mul_f32_e32 v79, v6, v6
	v_mul_f32_e32 v81, v7, v7
	s_waitcnt vmcnt(0)
	v_mul_f32_e32 v78, v11, v11
	v_mul_f32_e32 v80, v13, v13
	v_mov_b32_e32 v67, v82
	v_mov_b32_e32 v69, v83
	v_pk_add_f32 v[70:71], v[70:71], v[72:73]
	v_pk_add_f32 v[64:65], v[64:65], v[76:77]
	v_mul_f32_e32 v84, v2, v2
	v_mul_f32_e32 v85, v3, v3
	v_mul_f32_e32 v86, v4, v4
	v_mul_f32_e32 v87, v5, v5
	v_pk_fma_f32 v[62:63], v[10:11], v[10:11], v[78:79] op_sel_hi:[1,1,0]
	v_pk_fma_f32 v[74:75], v[12:13], v[12:13], v[80:81] op_sel_hi:[1,1,0]
	v_pk_add_f32 v[60:61], v[60:61], v[60:61] op_sel:[0,1] op_sel_hi:[1,0]
	v_pk_add_f32 v[58:59], v[58:59], v[58:59] op_sel:[0,1] op_sel_hi:[1,0]
	v_pk_add_f32 v[66:67], v[66:67], v[68:69]
	v_pk_add_f32 v[68:69], v[70:71], v[70:71] op_sel:[0,1] op_sel_hi:[1,0]
	v_pk_add_f32 v[64:65], v[64:65], v[64:65] op_sel:[0,1] op_sel_hi:[1,0]
	v_mov_b32_e32 v63, v86
	v_mov_b32_e32 v75, v87
	v_mov_b32_e32 v61, v79
	v_mov_b32_e32 v59, v81
	v_mov_b32_e32 v69, v84
	v_mov_b32_e32 v65, v85
	v_pk_add_f32 v[62:63], v[62:63], v[74:75]
	v_pk_add_f32 v[58:59], v[60:61], v[58:59]
	v_pk_add_f32 v[60:61], v[68:69], v[64:65]
	v_pk_add_f32 v[58:59], v[58:59], v[66:67]
	v_pk_add_f32 v[60:61], v[60:61], v[62:63]
	v_mov_b32_e32 v63, v58
	v_mov_b32_e32 v62, v60
	v_mov_b32_e32 v58, v61
	v_pk_add_f32 v[58:59], v[62:63], v[58:59]
	ds_bpermute_b32 v61, v53, v59
	ds_bpermute_b32 v60, v53, v58
	v_cndmask_b32_e32 v53, v1, v47, vcc
	v_lshlrev_b32_e32 v53, 2, v53
	v_cmp_lt_i32_e32 vcc, v48, v43
	s_waitcnt lgkmcnt(0)
	v_pk_add_f32 v[58:59], v[58:59], v[60:61]
	ds_bpermute_b32 v61, v53, v59
	ds_bpermute_b32 v60, v53, v58
	v_cndmask_b32_e32 v53, v1, v48, vcc
	v_lshlrev_b32_e32 v53, 2, v53
	v_cmp_lt_i32_e32 vcc, v49, v43
	s_waitcnt lgkmcnt(0)
	v_pk_add_f32 v[58:59], v[58:59], v[60:61]
	ds_bpermute_b32 v61, v53, v59
	ds_bpermute_b32 v60, v53, v58
	v_cndmask_b32_e32 v53, v1, v49, vcc
	v_lshlrev_b32_e32 v53, 2, v53
	v_cmp_lt_i32_e32 vcc, v50, v43
	s_waitcnt lgkmcnt(0)
	v_pk_add_f32 v[58:59], v[58:59], v[60:61]
	ds_bpermute_b32 v61, v53, v59
	ds_bpermute_b32 v60, v53, v58
	v_cndmask_b32_e32 v53, v1, v50, vcc
	v_lshlrev_b32_e32 v53, 2, v53
	v_cmp_lt_i32_e32 vcc, v51, v43
	s_waitcnt lgkmcnt(0)
	v_pk_add_f32 v[58:59], v[58:59], v[60:61]
	ds_bpermute_b32 v61, v53, v59
	ds_bpermute_b32 v60, v53, v58
	v_cndmask_b32_e32 v53, v1, v51, vcc
	v_lshlrev_b32_e32 v53, 2, v53
	s_waitcnt lgkmcnt(0)
	v_pk_add_f32 v[58:59], v[58:59], v[60:61]
	ds_bpermute_b32 v61, v53, v59
	ds_bpermute_b32 v60, v53, v58
	s_waitcnt lgkmcnt(0)
	v_pk_add_f32 v[58:59], v[58:59], v[60:61]
	s_nop 0
	v_pk_fma_f32 v[58:59], v[58:59], s[24:25], v[42:43] op_sel_hi:[1,0,0]
	s_nop 0
	v_mul_f32_e32 v53, 0x4b800000, v59
	v_cmp_gt_f32_e32 vcc, s1, v59
	v_mul_f32_e32 v60, 0x4b800000, v58
	v_cmp_gt_f32_e64 s[2:3], s1, v58
	v_cndmask_b32_e32 v53, v59, v53, vcc
	v_rsq_f32_e32 v53, v53
	v_cndmask_b32_e64 v58, v58, v60, s[2:3]
	v_rsq_f32_e32 v60, v58
	v_lshl_add_u64 v[58:59], s[16:17], 0, v[36:37]
	v_mul_f32_e32 v61, 0x45800000, v53
	v_cndmask_b32_e32 v53, v53, v61, vcc
	v_mul_f32_e32 v30, v30, v53
	v_mul_f32_e32 v32, v32, v53
	v_mul_f32_e32 v31, v31, v53
	v_mul_f32_e32 v33, v33, v53
	v_mul_f32_e32 v30, v88, v30
	v_mul_f32_e32 v32, v90, v32
	v_mul_f32_e32 v62, 0x45800000, v60
	v_mul_f32_e32 v31, v89, v31
	v_mul_f32_e32 v33, v91, v33
	v_bfe_u32 v61, v30, 16, 1
	v_bfe_u32 v63, v32, 16, 1
	v_cndmask_b32_e64 v60, v60, v62, s[2:3]
	v_bfe_u32 v62, v31, 16, 1
	v_bfe_u32 v64, v33, 16, 1
	v_add3_u32 v30, v30, v61, s28
	v_add3_u32 v32, v32, v63, s28
	v_add3_u32 v31, v31, v62, s28
	v_add3_u32 v33, v33, v64, s28
	v_lshrrev_b32_e32 v30, 16, v30
	v_lshrrev_b32_e32 v32, 16, v32
	v_and_or_b32 v30, v31, s5, v30
	v_and_or_b32 v31, v33, s5, v32
	v_add_co_u32_e32 v32, vcc, s29, v44
	v_mul_f32_e32 v26, v26, v60
	s_nop 0
	v_addc_co_u32_e32 v33, vcc, 0, v45, vcc
	v_mul_f32_e32 v26, v88, v26
	v_mul_f32_e32 v27, v27, v60
	global_store_dwordx2 v[32:33], v[30:31], off
	v_mul_f32_e32 v27, v89, v27
	v_bfe_u32 v30, v26, 16, 1
	v_add3_u32 v26, v26, v30, s28
	v_bfe_u32 v30, v27, 16, 1
	v_lshrrev_b32_e32 v26, 16, v26
	v_add3_u32 v27, v27, v30, s28
	v_and_or_b32 v26, v27, s5, v26
	v_mul_f32_e32 v27, v28, v60
	v_mul_f32_e32 v27, v90, v27
	v_mul_f32_e32 v28, v29, v60
	v_mul_f32_e32 v28, v91, v28
	v_bfe_u32 v29, v27, 16, 1
	v_add3_u32 v27, v27, v29, s28
	v_bfe_u32 v29, v28, 16, 1
	v_lshrrev_b32_e32 v27, 16, v27
	v_add3_u32 v28, v28, v29, s28
	v_add_co_u32_e32 v30, vcc, s29, v58
	v_and_or_b32 v27, v28, s5, v27
	s_nop 0
	v_addc_co_u32_e32 v31, vcc, 0, v59, vcc
	global_store_dwordx2 v[30:31], v[26:27], off
	v_mul_f32_e32 v22, v22, v53
	v_mul_f32_e32 v24, v24, v53
	v_mul_f32_e32 v23, v23, v53
	v_mul_f32_e32 v25, v25, v53
	v_mul_f32_e32 v18, v18, v60
	v_mul_f32_e32 v19, v19, v60
	v_mul_f32_e32 v20, v20, v60
	v_mul_f32_e32 v21, v21, v60
	v_mul_f32_e32 v14, v14, v53
	v_mul_f32_e32 v16, v16, v53
	v_mul_f32_e32 v15, v15, v53
	v_mul_f32_e32 v17, v17, v53
	v_mul_f32_e32 v10, v10, v60
	v_mul_f32_e32 v11, v11, v60
	v_mul_f32_e32 v12, v12, v60
	v_mul_f32_e32 v13, v13, v60
	v_mul_f32_e32 v6, v6, v53
	v_mul_f32_e32 v8, v8, v53
	v_pk_mul_f32 v[2:3], v[2:3], v[60:61] op_sel_hi:[1,0]
	v_mul_f32_e32 v7, v7, v53
	v_mul_f32_e32 v9, v9, v53
	v_pk_mul_f32 v[4:5], v[4:5], v[60:61] op_sel_hi:[1,0]
	s_lshl_b64 s[2:3], s[26:27], 10
	v_mul_f32_e32 v22, v22, v92
	v_mul_f32_e32 v24, v24, v94
	v_mul_f32_e32 v23, v23, v93
	v_mul_f32_e32 v25, v25, v95
	v_mul_f32_e32 v18, v92, v18
	v_mul_f32_e32 v19, v93, v19
	v_mul_f32_e32 v20, v94, v20
	v_bfe_u32 v26, v22, 16, 1
	v_bfe_u32 v28, v24, 16, 1
	v_mul_f32_e32 v21, v95, v21
	v_bfe_u32 v27, v23, 16, 1
	v_bfe_u32 v29, v25, 16, 1
	v_bfe_u32 v44, v18, 16, 1
	v_bfe_u32 v45, v19, 16, 1
	v_bfe_u32 v54, v20, 16, 1
	v_add3_u32 v22, v22, v26, s28
	v_add3_u32 v24, v24, v28, s28
	v_bfe_u32 v55, v21, 16, 1
	v_add3_u32 v23, v23, v27, s28
	v_add3_u32 v25, v25, v29, s28
	v_add3_u32 v18, v18, v44, s28
	v_add3_u32 v26, v19, v45, s28
	v_add3_u32 v19, v20, v54, s28
	v_lshrrev_b32_e32 v20, 16, v22
	v_lshrrev_b32_e32 v22, 16, v24
	v_add3_u32 v21, v21, v55, s28
	v_lshrrev_b32_e32 v24, 16, v18
	v_lshrrev_b32_e32 v27, 16, v19
	v_and_or_b32 v18, v23, s5, v20
	v_and_or_b32 v19, v25, s5, v22
	v_and_or_b32 v20, v26, s5, v24
	v_and_or_b32 v21, v21, s5, v27
	global_store_dwordx2 v[32:33], v[18:19], off offset:512
	global_store_dwordx2 v[30:31], v[20:21], off offset:512
	v_mul_f32_e32 v14, v14, v96
	v_mul_f32_e32 v16, v16, v98
	v_mul_f32_e32 v15, v15, v97
	v_mul_f32_e32 v17, v17, v99
	v_mul_f32_e32 v10, v96, v10
	v_mul_f32_e32 v11, v97, v11
	v_mul_f32_e32 v12, v98, v12
	v_bfe_u32 v18, v14, 16, 1
	v_bfe_u32 v20, v16, 16, 1
	v_mul_f32_e32 v13, v99, v13
	v_bfe_u32 v19, v15, 16, 1
	v_bfe_u32 v21, v17, 16, 1
	v_bfe_u32 v22, v10, 16, 1
	v_bfe_u32 v23, v11, 16, 1
	v_bfe_u32 v24, v12, 16, 1
	v_add3_u32 v14, v14, v18, s28
	v_add3_u32 v16, v16, v20, s28
	v_bfe_u32 v25, v13, 16, 1
	v_add3_u32 v15, v15, v19, s28
	v_add3_u32 v17, v17, v21, s28
	v_add3_u32 v10, v10, v22, s28
	v_add3_u32 v18, v11, v23, s28
	v_add3_u32 v11, v12, v24, s28
	v_lshrrev_b32_e32 v12, 16, v14
	v_lshrrev_b32_e32 v14, 16, v16
	v_add3_u32 v13, v13, v25, s28
	v_lshrrev_b32_e32 v16, 16, v10
	v_lshrrev_b32_e32 v19, 16, v11
	v_and_or_b32 v10, v15, s5, v12
	v_and_or_b32 v11, v17, s5, v14
	v_and_or_b32 v12, v18, s5, v16
	v_and_or_b32 v13, v13, s5, v19
	global_store_dwordx2 v[32:33], v[10:11], off offset:1024
	global_store_dwordx2 v[30:31], v[12:13], off offset:1024
	v_mul_f32_e32 v6, v6, v100
	v_mul_f32_e32 v8, v8, v102
	v_pk_mul_f32 v[2:3], v[2:3], v[100:101]
	v_mul_f32_e32 v7, v7, v101
	v_mul_f32_e32 v9, v9, v103
	v_bfe_u32 v10, v6, 16, 1
	v_bfe_u32 v14, v8, 16, 1
	v_and_b32_sdwa v17, v2, v52 dst_sel:DWORD dst_unused:UNUSED_PAD src0_sel:WORD_1 src1_sel:DWORD
	v_bfe_u32 v11, v7, 16, 1
	v_bfe_u32 v15, v9, 16, 1
	v_and_b32_sdwa v16, v3, v52 dst_sel:DWORD dst_unused:UNUSED_PAD src0_sel:WORD_1 src1_sel:DWORD
	v_add3_u32 v6, v6, v10, s28
	v_add3_u32 v8, v8, v14, s28
	v_add3_u32 v2, v2, v17, s28
	v_add3_u32 v7, v7, v11, s28
	v_add3_u32 v9, v9, v15, s28
	v_add3_u32 v3, v3, v16, s28
	v_lshrrev_b32_e32 v6, 16, v6
	v_lshrrev_b32_e32 v8, 16, v8
	v_lshrrev_b32_e32 v2, 16, v2
	v_and_or_b32 v6, v7, s5, v6
	v_and_or_b32 v7, v9, s5, v8
	v_and_or_b32 v2, v3, s5, v2
	v_pk_mul_f32 v[4:5], v[4:5], v[102:103]
	global_store_dwordx2 v[32:33], v[6:7], off offset:1536
	s_branch .LBB0_44
